# in-projection GEMM epilogue: n=0/n=1 bf16 column groups exchanged with v_permlane16_swap and stored as 16 dwordx4 instead of 32 dwordx2 per wave
# speedup vs baseline: 1.0110x; 1.0110x over previous
.LBB0_368:
	s_and_b32 s16, s8, 3
	s_lshl_b32 s17, s13, 13
	s_lshl_b32 s19, s16, 12
	s_add_u32 s8, s4, 0xa5b8000
	s_mov_b64 s[10:11], 0x80
	s_addc_u32 s9, s5, 0
	s_add_i32 m0, s39, 0x18000
	v_lshl_add_u64 v[8:9], v[8:9], 0, s[10:11]
	s_ashr_i32 s44, s33, 31
	s_waitcnt vmcnt(4)
	s_barrier
	global_load_lds_dwordx4 v[8:9], off
	v_lshl_add_u64 v[6:7], v[6:7], 0, s[10:11]
	s_add_i32 m0, s39, 0x1a000
	s_add_i32 s45, s39, 0x8000
	s_add_i32 s46, s39, 0xa000
	global_load_lds_dwordx4 v[6:7], off
	v_lshl_add_u64 v[4:5], v[4:5], 0, s[10:11]
	s_mov_b32 m0, s45
	s_add_u32 s14, s26, 0x80080
	global_load_lds_dwordx4 v[4:5], off
	v_lshl_add_u64 v[2:3], v[2:3], 0, s[10:11]
	s_mov_b32 m0, s46
	s_addc_u32 s15, s27, 0
	global_load_lds_dwordx4 v[2:3], off
	s_add_i32 m0, s39, 0x1c000
	v_lshl_add_u64 v[2:3], s[14:15], 0, v[130:131]
	global_load_lds_dwordx4 v[2:3], off
	v_lshl_add_u64 v[2:3], s[14:15], 0, v[132:133]
	s_add_i32 m0, s39, 0x1e000
	v_bfe_u32 v4, v10, 4, 2
	global_load_lds_dwordx4 v[2:3], off
	v_and_b32_e32 v3, 15, v10
	v_lshlrev_b32_e32 v2, 4, v4
	v_lshlrev_b32_e32 v6, 2, v10
	v_and_b32_e32 v6, 32, v6
	v_lshl_or_b32 v146, s13, 6, v3
	v_lshl_or_b32 v3, v3, 6, v2
	s_sext_i32_i8 s50, s12
	v_lshlrev_b32_e32 v5, 6, v10
	s_movk_i32 s12, 0x3c0
	v_bitop3_b32 v7, v3, s17, v6 bitop3:0xde
	v_mov_b32_e32 v3, v131
	v_and_or_b32 v5, v5, s12, v2
	v_lshl_add_u64 v[2:3], s[4:5], 0, v[2:3]
	s_mov_b64 s[4:5], 0x62b0000
	v_lshl_add_u64 v[134:135], v[2:3], 0, s[4:5]
	v_lshlrev_b32_e32 v2, 9, v10
	v_and_b32_e32 v2, 0x70000, v2
	v_lshlrev_b32_e32 v3, 12, v13
	v_or3_b32 v2, v11, v2, v3
	v_add_u32_e32 v136, v2, v12
	v_lshlrev_b32_e32 v2, 5, v14
	s_waitcnt vmcnt(6)
	s_cmp_eq_u32 s16, 0
	v_and_b32_e32 v2, 0xf0000, v2
	v_bitop3_b32 v147, s19, v5, v6 bitop3:0xf6
	v_lshlrev_b32_e32 v4, 2, v4
	s_cselect_b64 s[12:13], -1, 0
	v_or3_b32 v2, v11, v2, v3
	s_add_i32 s47, 0, 0x10000
	s_add_i32 s48, 0, 0x14000
	v_and_b32_e32 v144, 4, v4
	v_and_b32_e32 v145, 8, v4
	v_lshlrev_b32_e32 v144, 2, v144
	v_or_b32_e32 v144, v144, v145
	v_lshl_or_b32 v148, s16, 5, v144
	v_mov_b32_e32 v137, v131
	v_add_u32_e32 v138, v2, v12
	v_mov_b32_e32 v139, v131
	v_mov_b64_e32 v[140:141], 0x5ee
	v_mov_b64_e32 v[142:143], 0x5ed
	v_add_u32_e32 v149, s47, v147
	v_add_u32_e32 v150, 0, v7
	v_add_u32_e32 v151, s48, v147
	s_movk_i32 s49, 0x2c00
	s_barrier
	s_branch .LBB0_370

.LBB0_382:
	s_andn2_b64 vcc, exec, s[18:19]
	s_cbranch_vccnz .LBB0_369
	v_lshl_or_b32 v152, s50, 8, v148
	v_ashrrev_i32_e32 v153, 31, v152
	v_mov_b64_e32 v[154:155], s[8:9]
	v_lshlrev_b64 v[152:153], 1, v[152:153]
	v_lshl_add_u64 v[154:155], v[154:155], 0, v[152:153]
	v_mad_i64_i32 v[160:161], s[18:19], v144, s49, v[154:155]
	v_or_b32_e32 v156, 16, v144
	v_mad_i64_i32 v[162:163], s[18:19], v156, s49, v[154:155]
	v_or_b32_e32 v156, 32, v144
	v_mad_i64_i32 v[164:165], s[18:19], v156, s49, v[154:155]
	v_or_b32_e32 v156, 48, v144
	v_mad_i64_i32 v[166:167], s[18:19], v156, s49, v[154:155]
	v_add_u32_e32 v156, 0x80, v144
	v_mad_i64_i32 v[168:169], s[18:19], v156, s49, v[154:155]
	v_add_u32_e32 v156, 0x90, v144
	v_mad_i64_i32 v[170:171], s[18:19], v156, s49, v[154:155]
	v_add_u32_e32 v156, 0xa0, v144
	v_mad_i64_i32 v[172:173], s[18:19], v156, s49, v[154:155]
	v_add_u32_e32 v156, 0xb0, v144
	v_mad_i64_i32 v[174:175], s[18:19], v156, s49, v[154:155]
	v_cvt_pk_bf16_f32 v126, v126, v127
	v_cvt_pk_bf16_f32 v127, v128, v129
	v_cvt_pk_bf16_f32 v128, v122, v123
	v_cvt_pk_bf16_f32 v129, v124, v125
	v_cvt_pk_bf16_f32 v110, v110, v111
	v_cvt_pk_bf16_f32 v111, v112, v113
	v_cvt_pk_bf16_f32 v112, v106, v107
	v_cvt_pk_bf16_f32 v113, v108, v109
	v_permlane16_swap_b32_e32 v126, v128
	v_permlane16_swap_b32_e32 v127, v129
	global_store_dwordx4 v[160:161], v[126:129], off
	v_cvt_pk_bf16_f32 v118, v118, v119
	v_cvt_pk_bf16_f32 v119, v120, v121
	v_cvt_pk_bf16_f32 v120, v114, v115
	v_cvt_pk_bf16_f32 v121, v116, v117
	v_permlane16_swap_b32_e32 v110, v112
	v_permlane16_swap_b32_e32 v111, v113
	global_store_dwordx4 v[160:161], v[110:113], off offset:256
	v_cvt_pk_bf16_f32 v94, v94, v95
	v_cvt_pk_bf16_f32 v95, v96, v97
	v_cvt_pk_bf16_f32 v96, v90, v91
	v_cvt_pk_bf16_f32 v97, v92, v93
	v_permlane16_swap_b32_e32 v118, v120
	v_permlane16_swap_b32_e32 v119, v121
	global_store_dwordx4 v[162:163], v[118:121], off
	v_cvt_pk_bf16_f32 v102, v102, v103
	v_cvt_pk_bf16_f32 v103, v104, v105
	v_cvt_pk_bf16_f32 v104, v98, v99
	v_cvt_pk_bf16_f32 v105, v100, v101
	v_permlane16_swap_b32_e32 v94, v96
	v_permlane16_swap_b32_e32 v95, v97
	global_store_dwordx4 v[162:163], v[94:97], off offset:256
	v_cvt_pk_bf16_f32 v78, v78, v79
	v_cvt_pk_bf16_f32 v79, v80, v81
	v_cvt_pk_bf16_f32 v80, v74, v75
	v_cvt_pk_bf16_f32 v81, v76, v77
	v_permlane16_swap_b32_e32 v102, v104
	v_permlane16_swap_b32_e32 v103, v105
	global_store_dwordx4 v[164:165], v[102:105], off
	v_cvt_pk_bf16_f32 v86, v86, v87
	v_cvt_pk_bf16_f32 v87, v88, v89
	v_cvt_pk_bf16_f32 v88, v82, v83
	v_cvt_pk_bf16_f32 v89, v84, v85
	v_permlane16_swap_b32_e32 v78, v80
	v_permlane16_swap_b32_e32 v79, v81
	global_store_dwordx4 v[164:165], v[78:81], off offset:256
	v_cvt_pk_bf16_f32 v70, v70, v71
	v_cvt_pk_bf16_f32 v71, v72, v73
	v_cvt_pk_bf16_f32 v72, v66, v67
	v_cvt_pk_bf16_f32 v73, v68, v69
	v_permlane16_swap_b32_e32 v86, v88
	v_permlane16_swap_b32_e32 v87, v89
	global_store_dwordx4 v[166:167], v[86:89], off
	v_cvt_pk_bf16_f32 v62, v62, v63
	v_cvt_pk_bf16_f32 v63, v64, v65
	v_cvt_pk_bf16_f32 v64, v58, v59
	v_cvt_pk_bf16_f32 v65, v60, v61
	v_permlane16_swap_b32_e32 v70, v72
	v_permlane16_swap_b32_e32 v71, v73
	global_store_dwordx4 v[166:167], v[70:73], off offset:256
	v_cvt_pk_bf16_f32 v46, v46, v47
	v_cvt_pk_bf16_f32 v47, v48, v49
	v_cvt_pk_bf16_f32 v48, v42, v43
	v_cvt_pk_bf16_f32 v49, v44, v45
	v_permlane16_swap_b32_e32 v62, v64
	v_permlane16_swap_b32_e32 v63, v65
	global_store_dwordx4 v[168:169], v[62:65], off
	v_cvt_pk_bf16_f32 v54, v54, v55
	v_cvt_pk_bf16_f32 v55, v56, v57
	v_cvt_pk_bf16_f32 v56, v50, v51
	v_cvt_pk_bf16_f32 v57, v52, v53
	v_permlane16_swap_b32_e32 v46, v48
	v_permlane16_swap_b32_e32 v47, v49
	global_store_dwordx4 v[168:169], v[46:49], off offset:256
	v_cvt_pk_bf16_f32 v30, v30, v31
	v_cvt_pk_bf16_f32 v31, v32, v33
	v_cvt_pk_bf16_f32 v32, v26, v27
	v_cvt_pk_bf16_f32 v33, v28, v29
	v_permlane16_swap_b32_e32 v54, v56
	v_permlane16_swap_b32_e32 v55, v57
	global_store_dwordx4 v[170:171], v[54:57], off
	v_cvt_pk_bf16_f32 v38, v38, v39
	v_cvt_pk_bf16_f32 v39, v40, v41
	v_cvt_pk_bf16_f32 v40, v34, v35
	v_cvt_pk_bf16_f32 v41, v36, v37
	v_permlane16_swap_b32_e32 v30, v32
	v_permlane16_swap_b32_e32 v31, v33
	global_store_dwordx4 v[170:171], v[30:33], off offset:256
	v_cvt_pk_bf16_f32 v14, v14, v15
	v_cvt_pk_bf16_f32 v15, v16, v17
	v_cvt_pk_bf16_f32 v16, v10, v11
	v_cvt_pk_bf16_f32 v17, v12, v13
	v_permlane16_swap_b32_e32 v38, v40
	v_permlane16_swap_b32_e32 v39, v41
	global_store_dwordx4 v[172:173], v[38:41], off
	v_cvt_pk_bf16_f32 v22, v22, v23
	v_cvt_pk_bf16_f32 v23, v24, v25
	v_cvt_pk_bf16_f32 v24, v18, v19
	v_cvt_pk_bf16_f32 v25, v20, v21
	v_permlane16_swap_b32_e32 v14, v16
	v_permlane16_swap_b32_e32 v15, v17
	global_store_dwordx4 v[172:173], v[14:17], off offset:256
	v_cvt_pk_bf16_f32 v6, v6, v7
	v_cvt_pk_bf16_f32 v7, v8, v9
	v_cvt_pk_bf16_f32 v8, v2, v3
	v_cvt_pk_bf16_f32 v9, v4, v5
	v_permlane16_swap_b32_e32 v22, v24
	v_permlane16_swap_b32_e32 v23, v25
	global_store_dwordx4 v[174:175], v[22:25], off
	s_nop 1
	v_permlane16_swap_b32_e32 v6, v8
	v_permlane16_swap_b32_e32 v7, v9
	global_store_dwordx4 v[174:175], v[6:9], off offset:256
	s_branch .LBB0_369
